# chain + gla_prep v double-buffer + attention: deferred queue atomic, scalar sink load, first tile of an item waits vmcnt(8) instead of draining the previous item's 8 stores
# baseline (speedup 1.0000x reference)
; #define LAS __attribute__((address_space(3)))
; DI void phase_attn(const Params& P, int l, LAS unsigned char* lds) {
;     ...
;     unsigned* qctr = (unsigned*)(P.ws + WS_CTL) + 3584 + 64 * l;
;     volatile LAS int* slot = (volatile LAS int*)(lds + AT_END);
;     if (tid == 0) { const int a0 = (int)__hip_atomic_fetch_add(qctr, 1u, __ATOMIC_RELAXED, __HIP_MEMORY_SCOPE_AGENT); const int a1 = (int)__hip_atomic_fetch_add(qctr, 1u, __ATOMIC_RELAXED, __HIP_MEMORY_SCOPE_AGENT); slot[0] = a0; slot[1] = a1; }
;     __syncthreads();
;     int item = slot[0], inext = slot[1]; int pend = AT_NITEM;
;     if (item >= AT_NITEM) return;
;     int e = 0;
;     { const int n0 = (item >> 2) & 31; __syncthreads(); AT_ISSUE(item, n0 == 0 ? 1 : 0, 0); }
;     bf16x8 qr[8];
;     ...
;     AT_QLOAD(item);
.LBB0_469:
	s_or_b64 exec, exec, s[4:5]
	s_add_i32 s4, 0, 0x24000
	v_mov_b32_e32 v3, s4
	s_add_i32 s4, 0, 0x24004
	s_waitcnt lgkmcnt(0)
	s_barrier
	ds_read_b32 v3, v3
	v_mov_b32_e32 v5, s4
	ds_read_b32 v5, v5
	s_movk_i32 s4, 0x4ff
	s_mov_b32 s5, 0
	s_waitcnt lgkmcnt(1)
	v_cmp_lt_i32_e32 vcc, s4, v3
	v_readfirstlane_b32 s22, v3
	s_waitcnt lgkmcnt(0)
	v_readfirstlane_b32 s30, v5
	s_cbranch_vccnz .LBB0_501
	s_lshl_b32 s18, s13, 13
	s_lshl_b32 s4, s14, 14
	s_and_b32 s19, s18, 0x2000
	s_add_u32 s6, s50, s6
	s_addc_u32 s7, s51, s7
	s_add_u32 s8, s50, 0x3c40000
	s_addc_u32 s9, s51, 0
	s_add_u32 s10, s50, 0x1f940000
	s_addc_u32 s11, s51, 0
	s_ashr_i32 s14, s22, 7
	s_bfe_u32 s23, s22, 0x10001
	s_ashr_i32 s15, s14, 31
	s_add_i32 s20, 0, 0x8000
	s_bfe_u32 s21, s22, 0x50002
	s_mul_i32 s16, s23, 0xa000
	s_lshl_b64 s[14:15], s[14:15], 12
	s_add_u32 s24, s14, s16
	s_addc_u32 s25, s15, 0
	v_sub_co_u32_e64 v3, s[16:17], s21, 1
	s_nop 0
	v_readfirstlane_b32 s26, v3
	s_cmp_lg_u64 s[16:17], 0
	s_addc_u32 s16, s26, 0
	s_lshl_b32 s16, s16, 7
	s_ashr_i32 s17, s16, 31
	s_add_u32 s16, s24, s16
	s_addc_u32 s17, s25, s17
	s_lshl_b64 s[16:17], s[16:17], 8
	v_mov_b32_e32 v159, 0
	s_add_u32 s16, s6, s16
	s_addc_u32 s17, s7, s17
	s_add_i32 s31, s19, 0
	v_mov_b32_e32 v149, v159
	s_add_i32 s31, s31, s4
	v_lshlrev_b64 v[8:9], 1, v[148:149]
	v_lshl_add_u64 v[10:11], s[16:17], 0, v[8:9]
	s_mov_b32 m0, s31
	v_mov_b32_e32 v151, v159
	s_barrier
	global_load_lds_dwordx4 v[10:11], off
	v_lshlrev_b64 v[10:11], 1, v[150:151]
	v_lshl_add_u64 v[12:13], s[16:17], 0, v[10:11]
	s_add_i32 m0, s31, 0x400
	v_mov_b32_e32 v153, v159
	global_load_lds_dwordx4 v[12:13], off
	v_lshlrev_b64 v[12:13], 1, v[152:153]
	v_lshl_add_u64 v[14:15], s[16:17], 0, v[12:13]
	s_add_i32 m0, s31, 0x800
	v_mov_b32_e32 v155, v159
	global_load_lds_dwordx4 v[14:15], off
	v_lshlrev_b64 v[14:15], 1, v[154:155]
	v_lshl_add_u64 v[16:17], s[16:17], 0, v[14:15]
	s_add_i32 m0, s31, 0xc00
	v_mov_b32_e32 v157, v159
	global_load_lds_dwordx4 v[16:17], off
	v_lshlrev_b64 v[16:17], 1, v[156:157]
	v_lshl_add_u64 v[18:19], s[16:17], 0, v[16:17]
	s_add_i32 m0, s31, 0x1000
	v_mov_b32_e32 v3, v159
	global_load_lds_dwordx4 v[18:19], off
	v_lshlrev_b64 v[18:19], 1, v[158:159]
	v_lshl_add_u64 v[20:21], s[16:17], 0, v[18:19]
	s_add_i32 m0, s31, 0x1400
	v_lshlrev_b64 v[2:3], 1, v[2:3]
	v_mov_b32_e32 v5, v159
	global_load_lds_dwordx4 v[20:21], off
	v_lshl_add_u64 v[20:21], s[16:17], 0, v[2:3]
	s_add_i32 m0, s31, 0x1800
	v_lshlrev_b64 v[4:5], 1, v[4:5]
	s_lshr_b32 s35, s12, 8
	s_lshl_b32 s4, s13, 5
	global_load_lds_dwordx4 v[20:21], off
	v_lshl_add_u64 v[20:21], s[16:17], 0, v[4:5]
	s_lshl_b32 s16, s35, 6
	s_and_b32 s17, s4, 0x60
	s_xor_b32 s36, s17, s16
	s_lshl_b32 s4, s21, 7
	s_add_i32 m0, s31, 0x1c00
	s_add_i32 s37, s18, 0
	s_add_i32 s4, s4, s36
	s_add_u32 s4, s14, s4
	s_movk_i32 s34, 0x1400
	global_load_lds_dwordx4 v[20:21], off
	v_or_b32_e32 v7, s4, v1
	v_mov_b64_e32 v[20:21], s[8:9]
	v_mad_u64_u32 v[20:21], s[12:13], v7, s34, v[20:21]
	s_addc_u32 s14, s15, 0
	s_lshl_b32 s12, s22, 1
	s_and_b32 s12, s12, 2
	s_add_i32 s12, s12, s35
	v_mov_b32_e32 v207, 0x1400
	s_lshl_b32 s4, s23, 9
	s_lshl_b32 s12, s12, 7
	v_mad_i32_i24 v21, s14, v207, v21
	s_add_i32 s4, s12, s4
	v_lshl_add_u64 v[20:21], s[4:5], 1, v[20:21]
	v_mov_b32_e32 v147, v159
	v_lshl_add_u64 v[20:21], v[20:21], 0, v[146:147]
	global_load_dwordx4 v[98:101], v[20:21], off offset:224 nt
	global_load_dwordx4 v[102:105], v[20:21], off offset:192 nt
	global_load_dwordx4 v[106:109], v[20:21], off offset:160 nt
	global_load_dwordx4 v[110:113], v[20:21], off offset:128 nt
	global_load_dwordx4 v[114:117], v[20:21], off offset:96 nt
	global_load_dwordx4 v[118:121], v[20:21], off offset:64 nt
	global_load_dwordx4 v[122:125], v[20:21], off offset:32 nt
	global_load_dwordx4 v[126:129], v[20:21], off nt
	v_lshl_add_u64 v[168:169], s[6:7], 0, v[2:3]
	v_mov_b32_e32 v3, s16
	v_bitop3_b32 v3, s17, v1, v3 bitop3:0xde
	v_lshlrev_b32_e32 v7, 4, v137
	v_lshl_or_b32 v2, s35, 11, v146
	v_lshlrev_b32_e32 v3, 2, v3
	v_and_b32_e32 v21, 0xc0, v7
	v_lshlrev_b32_e32 v22, 1, v137
	s_movk_i32 s39, 0x70
	v_sub_u32_e32 v2, v2, v3
	s_movk_i32 s38, 0xc0
	v_and_b32_e32 v20, 0x78, v6
	v_and_b32_e32 v6, 0x118, v6
	v_and_b32_e32 v23, 0x70, v7
	v_bitop3_b32 v147, v146, v7, s39 bitop3:0x78
	s_movk_i32 s40, 0x60
	s_movk_i32 s41, 0x80
	s_movk_i32 s42, 0xa0
	s_movk_i32 s43, 0xe0
	v_and_or_b32 v7, v22, 32, v21
	v_add_u32_e32 v216, 0, v2
	v_mbcnt_lo_u32_b32 v2, -1, 0
	v_lshlrev_b32_e32 v160, 3, v202
	v_lshrrev_b32_e32 v162, 4, v161
	v_bitop3_b32 v208, v146, v23, 32 bitop3:0x36
	v_bitop3_b32 v209, v146, v23, 64 bitop3:0x36
	v_bitop3_b32 v210, v146, v23, s40 bitop3:0x36
	v_bitop3_b32 v211, v146, v23, s41 bitop3:0x36
	v_bitop3_b32 v212, v146, v23, s42 bitop3:0x36
	v_bitop3_b32 v213, v146, v23, s38 bitop3:0x36
	v_bitop3_b32 v214, v146, v23, s43 bitop3:0x36
	v_add3_u32 v215, v6, s20, v7
	v_lshl_add_u64 v[164:165], s[6:7], 0, v[4:5]
	v_lshl_add_u64 v[166:167], s[6:7], 0, v[18:19]
	v_lshl_add_u64 v[170:171], s[6:7], 0, v[8:9]
	v_lshl_add_u64 v[172:173], s[6:7], 0, v[10:11]
	v_lshl_add_u64 v[174:175], s[6:7], 0, v[12:13]
	v_lshl_add_u64 v[176:177], s[6:7], 0, v[14:15]
	v_lshl_add_u64 v[178:179], s[6:7], 0, v[16:17]
	v_mov_b32_e32 v218, 0x500
	v_lshlrev_b32_e32 v158, 1, v20
	s_mov_b64 s[12:13], 0xac00
	s_mov_b64 s[14:15], 0xfc00
	s_add_i32 s44, 0, 0x24008
	s_mov_b32 s45, 0x10000
	s_mov_b32 s74, 0xf149f2ca
	s_mov_b32 s75, 0x41000000
	s_movk_i32 s76, 0x4000
	s_mov_b32 s77, 0x14000
	s_movk_i32 s78, 0x50
	s_movk_i32 s79, 0x90
	s_movk_i32 s80, 0xb0
	s_movk_i32 s81, 0xd0
	s_movk_i32 s82, 0xf0
	s_mov_b32 s83, 0xc000
	s_mov_b32 s84, 0x18000
	v_mbcnt_hi_u32_b32 v217, -1, v2
	s_mov_b32 s85, 0
	s_waitcnt vmcnt(0)
	s_branch .LBB0_472

; #define LAS __attribute__((address_space(3)))
; DI void phase_attn(const Params& P, int l, LAS unsigned char* lds) {
;     ...
;     for (; item < AT_NITEM; ) {
;         const int half = item & 1, hk = (item >> 1) & 1, n = (item >> 2) & 31, sq = item >> 7;
;         const int g = hk * 4 + half * 2 + (wid >> 2), rq = n * 128 + ((wid & 3) ^ ((wid >> 2) << 1)) * 32;
;         const size_t tok = (size_t)sq * SEQL + rq + r32;
;         float m_run = P.sink[l * 8 + g] * LOG2E, l_run = 1.f;
;         f32x16 o[4]; for (int d = 0; d < 4; ++d) for (int i = 0; i < 16; ++i) o[d][i] = 0.f;
;         const int t_lo = n == 0 ? 1 : 0, t_hi = n == 31 ? 2 : 3;
;         const size_t tokw = (size_t)sq * SEQL + rq;
;         const bf16_t* zp = PA + (tokw + (lane >> 4)) * 2560 + 1536 + g * 128 + (lane & 15) * 8; u32x4 zz[8];
;         const LAS float* tg = tab + g * 512 + 96 + 128 - r32;
;         for (int t = t_lo; t < t_hi; ++t, ++e) {
.LBB0_472:
	s_lshl_b32 s16, s22, 1
	s_bfe_u32 s23, s22, 0x10001
	s_and_b32 s16, s16, 2
	s_lshl_b32 s4, s23, 2
	s_add_i32 s16, s16, s35
	s_add_i32 s4, s16, s4
	s_lshl_b32 s16, s4, 2
	s_mov_b32 s67, s16
	v_mov_b32_e32 v2, s16
	v_readlane_b32 s16, v254, 0
	v_readlane_b32 s17, v254, 1
	s_bfe_u32 s64, s22, 0x50002
	s_lshl_b32 s71, s64, 7
	s_add_i32 s90, s71, s36
	v_readlane_b32 s18, v254, 2
	v_readlane_b32 s19, v254, 3
	s_nop 4
	s_load_dword s68, s[16:17], s67
	s_ashr_i32 s16, s22, 7
	s_ashr_i32 s17, s16, 31
	s_lshl_b64 s[24:25], s[16:17], 12
	s_add_u32 s16, s24, s90
	v_mov_b64_e32 v[2:3], s[8:9]
	s_addc_u32 s18, s25, 0
	v_or_b32_e32 v180, s16, v162
	s_cmp_eq_u32 s64, 31
	v_mad_u64_u32 v[2:3], s[16:17], v180, s34, v[2:3]
	s_cselect_b32 s87, 2, 3
	s_lshl_b32 s86, s4, 7
	s_lshl_b32 s4, s4, 8
	v_mad_i32_i24 v3, s18, v207, v3
	s_cmp_eq_u32 s64, 0
	v_lshl_add_u64 v[2:3], v[2:3], 0, s[4:5]
	s_cselect_b64 s[26:27], -1, 0
	v_lshl_add_u64 v[2:3], v[2:3], 0, v[158:159]
	s_mov_b64 s[16:17], 0xc00
	v_lshl_add_u64 v[182:183], v[2:3], 0, s[16:17]
	s_and_b64 s[16:17], s[26:27], exec
	s_cselect_b32 s66, -2, -1
	s_cmpk_lt_i32 s30, 0x500
	s_mov_b64 s[16:17], 0x5c00
	s_cselect_b64 s[20:21], -1, 0
	s_cmpk_gt_i32 s30, 0x4ff
	v_mov_b32_e32 v181, s18
	v_lshl_add_u64 v[184:185], v[2:3], 0, s[16:17]
	s_cselect_b64 s[16:17], -1, 0
	s_ashr_i32 s18, s30, 7
	s_bfe_i32 s19, s30, 0x10001
	s_and_b32 s29, s19, 0xa000
	s_ashr_i32 s19, s18, 31
	s_bfe_u32 s28, s30, 0x50002
	s_lshl_b64 s[18:19], s[18:19], 12
	v_lshl_add_u64 v[186:187], v[2:3], 0, s[12:13]
	v_lshl_add_u64 v[188:189], v[2:3], 0, s[14:15]
	v_sub_co_u32_e64 v2, vcc, s28, 1
	s_add_u32 s28, s29, s18
	s_mul_i32 s65, s23, 0xa000
	s_addc_u32 s29, 0, s19
	s_add_i32 s89, s90, 0xffffff80
	s_addk_i32 s90, 0x9f
	s_lshl_b32 s91, s85, 16
	v_addc_co_u32_e32 v2, vcc, 0, v2, vcc
	s_add_u32 s24, s65, s24
	v_lshlrev_b32_e32 v2, 7, v2
	s_addc_u32 s25, s25, 0
	v_ashrrev_i32_e32 v3, 31, v2
	s_cmp_lg_u64 s[26:27], 0
	v_lshl_add_u64 v[2:3], s[28:29], 0, v[2:3]
	s_addc_u32 s28, s64, 0
	s_lshl_b32 s28, s28, 7
	s_add_u32 s24, s24, s28
	s_addc_u32 s25, s25, 0
	s_and_b32 s29, s22, 1
	v_cndmask_b32_e64 v5, 0, 1, s[26:27]
	v_lshlrev_b64 v[190:191], 8, v[2:3]
	s_lshl_b32 s28, s23, 13
	s_lshl_b64 s[22:23], s[24:25], 8
	s_lshl_b32 s24, s29, 12
	v_lshlrev_b32_e32 v6, 9, v5
	v_lshl_add_u64 v[2:3], s[6:7], 0, v[190:191]
	s_or_b32 s24, s28, s24
	v_lshl_add_u64 v[192:193], v[148:149], 1, v[2:3]
	v_lshl_add_u64 v[194:195], v[150:151], 1, v[2:3]
	v_lshl_add_u64 v[196:197], v[152:153], 1, v[2:3]
	v_lshl_add_u64 v[198:199], v[154:155], 1, v[2:3]
	v_lshl_add_u64 v[200:201], v[156:157], 1, v[2:3]
	v_or_b32_e32 v2, s24, v6
	v_readfirstlane_b32 s4, v5
	s_cmp_lg_u64 s[26:27], 0
	v_add_u32_e32 v219, v216, v2
	v_subrev_u32_e32 v2, s87, v5
	v_mov_b32_e32 v16, v159
	v_mov_b32_e32 v17, v159
	s_addc_u32 s92, s66, 0
	s_waitcnt lgkmcnt(0)
	v_mov_b32_e32 v4, s68
	v_mul_f32_e32 v220, 0x3fb8aa3b, v4
	v_add_u32_e32 v221, 1, v2
	s_lshl_b32 s24, s4, 7
	v_mov_b32_e32 v2, v159
	v_mov_b32_e32 v3, v159
	v_mov_b32_e32 v4, v159
	v_mov_b32_e32 v5, v159
	v_mov_b32_e32 v6, v159
	v_mov_b32_e32 v7, v159
	v_mov_b32_e32 v8, v159
	v_mov_b32_e32 v9, v159
	v_mov_b32_e32 v10, v159
	v_mov_b32_e32 v11, v159
	v_mov_b32_e32 v12, v159
	v_mov_b32_e32 v13, v159
	v_mov_b32_e32 v14, v159
	v_mov_b32_e32 v15, v159
	v_mov_b64_e32 v[32:33], v[16:17]
	v_mov_b64_e32 v[48:49], v[16:17]
	v_mov_b64_e32 v[64:65], v[16:17]
	s_mov_b32 s70, 0
	s_add_i32 s93, s24, 0xffffff80
	v_mov_b32_e32 v222, 1.0
	s_mov_b32 s88, 0
	v_mov_b64_e32 v[30:31], v[14:15]
	v_mov_b64_e32 v[28:29], v[12:13]
	v_mov_b64_e32 v[26:27], v[10:11]
	v_mov_b64_e32 v[24:25], v[8:9]
	v_mov_b64_e32 v[22:23], v[6:7]
	v_mov_b64_e32 v[20:21], v[4:5]
	v_mov_b64_e32 v[18:19], v[2:3]
	v_mov_b64_e32 v[46:47], v[14:15]
	v_mov_b64_e32 v[44:45], v[12:13]
	v_mov_b64_e32 v[42:43], v[10:11]
	v_mov_b64_e32 v[40:41], v[8:9]
	v_mov_b64_e32 v[38:39], v[6:7]
	v_mov_b64_e32 v[36:37], v[4:5]
	v_mov_b64_e32 v[34:35], v[2:3]
	v_mov_b64_e32 v[62:63], v[14:15]
	v_mov_b64_e32 v[60:61], v[12:13]
	v_mov_b64_e32 v[58:59], v[10:11]
	v_mov_b64_e32 v[56:57], v[8:9]
	v_mov_b64_e32 v[54:55], v[6:7]
	v_mov_b64_e32 v[52:53], v[4:5]
	v_mov_b64_e32 v[50:51], v[2:3]
	s_waitcnt vmcnt(8)
	s_add_i32 s24, s92, s88
	s_branch .Lat_first_0

; DI void phase_attn(const Params& P, int l, LAS unsigned char* lds) {
;     ...
;             asm volatile("s_waitcnt vmcnt(0)" ::: "memory");
;             if (t == t_lo + 1 && tid == 0) slot[2] = pend;
;             asm volatile("s_waitcnt lgkmcnt(0)" ::: "memory");
;             __builtin_amdgcn_s_barrier();
;             asm volatile("" ::: "memory");
;             if (t == t_lo && tid == 0) pend = (int)__hip_atomic_fetch_add(qctr, 1u, __ATOMIC_RELAXED, __HIP_MEMORY_SCOPE_AGENT);
.Lat_first_0:
	s_cmp_eq_u32 s24, 0
	s_cselect_b64 s[24:25], -1, 0
	s_and_b64 s[26:27], s[0:1], s[24:25]
	s_and_saveexec_b64 s[24:25], s[26:27]
	v_mov_b32_e32 v66, s44
	v_mov_b32_e32 v218, v255
	ds_write_b32 v66, v218
	s_or_b64 exec, exec, s[24:25]
	s_waitcnt lgkmcnt(0)
	s_barrier
	s_cmp_eq_u32 s70, 0
	s_cselect_b64 s[24:25], -1, 0
	s_and_b64 s[26:27], s[0:1], s[24:25]
	s_and_saveexec_b64 s[24:25], s[26:27]
	s_cbranch_execz .LBB0_481
	s_mov_b64 s[28:29], exec
	v_mbcnt_lo_u32_b32 v66, s28, 0
	v_mbcnt_hi_u32_b32 v66, s29, v66
	v_cmp_eq_u32_e32 vcc, 0, v66
	s_and_saveexec_b64 s[26:27], vcc
	s_cbranch_execz .LBB0_480
	s_bcnt1_i32_b64 s28, s[28:29]
	v_mov_b32_e32 v67, s28
	global_atomic_add v255, v159, v67, s[2:3] sc0

; #define LAS __attribute__((address_space(3)))
; DI void phase_attn(const Params& P, int l, LAS unsigned char* lds) {
;     ...
;     unsigned* qctr = (unsigned*)(P.ws + WS_CTL) + 3584 + 64 * l;
;     volatile LAS int* slot = (volatile LAS int*)(lds + AT_END);
;     if (tid == 0) { const int a0 = (int)__hip_atomic_fetch_add(qctr, 1u, __ATOMIC_RELAXED, __HIP_MEMORY_SCOPE_AGENT); const int a1 = (int)__hip_atomic_fetch_add(qctr, 1u, __ATOMIC_RELAXED, __HIP_MEMORY_SCOPE_AGENT); slot[0] = a0; slot[1] = a1; }
;     __syncthreads();
;     int item = slot[0], inext = slot[1]; int pend = AT_NITEM;
;     if (item >= AT_NITEM) return;
;     int e = 0;
;     { const int n0 = (item >> 2) & 31; __syncthreads(); AT_ISSUE(item, n0 == 0 ? 1 : 0, 0); }
;     bf16x8 qr[8];
;     ...
;     AT_QLOAD(item);
.LBB0_1031:
	s_or_b64 exec, exec, s[4:5]
	s_add_i32 s4, 0, 0x24000
	v_mov_b32_e32 v3, s4
	s_add_i32 s4, 0, 0x24004
	s_waitcnt lgkmcnt(0)
	s_barrier
	ds_read_b32 v3, v3
	v_mov_b32_e32 v5, s4
	ds_read_b32 v5, v5
	s_movk_i32 s4, 0x4ff
	s_mov_b32 s5, 0
	s_waitcnt lgkmcnt(1)
	v_cmp_lt_i32_e32 vcc, s4, v3
	v_readfirstlane_b32 s26, v3
	s_waitcnt lgkmcnt(0)
	v_readfirstlane_b32 s36, v5
	s_cbranch_vccnz .LBB0_1063
	s_lshl_b32 s18, s13, 13
	s_lshl_b32 s4, s14, 14
	s_and_b32 s19, s18, 0x2000
	s_add_u32 s6, s50, s6
	s_addc_u32 s7, s51, s7
	s_add_u32 s8, s50, 0x3c40000
	s_addc_u32 s9, s51, 0
	s_add_u32 s10, s50, 0x1f940000
	s_addc_u32 s11, s51, 0
	s_ashr_i32 s14, s26, 7
	s_bfe_u32 s22, s26, 0x10001
	s_ashr_i32 s15, s14, 31
	s_add_i32 s20, 0, 0x8000
	s_bfe_u32 s21, s26, 0x50002
	s_mul_i32 s16, s22, 0xa000
	s_lshl_b64 s[14:15], s[14:15], 12
	s_add_u32 s23, s14, s16
	s_addc_u32 s24, s15, 0
	v_sub_co_u32_e64 v3, s[16:17], s21, 1
	s_nop 0
	v_readfirstlane_b32 s25, v3
	s_cmp_lg_u64 s[16:17], 0
	s_addc_u32 s16, s25, 0
	s_lshl_b32 s16, s16, 7
	s_ashr_i32 s17, s16, 31
	s_add_u32 s16, s23, s16
	s_addc_u32 s17, s24, s17
	s_lshl_b64 s[16:17], s[16:17], 8
	v_mov_b32_e32 v159, 0
	s_add_u32 s16, s6, s16
	s_addc_u32 s17, s7, s17
	s_add_i32 s37, s19, 0
	v_mov_b32_e32 v149, v159
	s_add_i32 s37, s37, s4
	v_lshlrev_b64 v[8:9], 1, v[148:149]
	v_lshl_add_u64 v[10:11], s[16:17], 0, v[8:9]
	s_mov_b32 m0, s37
	v_mov_b32_e32 v151, v159
	s_barrier
	global_load_lds_dwordx4 v[10:11], off
	v_lshlrev_b64 v[10:11], 1, v[150:151]
	v_lshl_add_u64 v[12:13], s[16:17], 0, v[10:11]
	s_add_i32 m0, s37, 0x400
	v_mov_b32_e32 v153, v159
	global_load_lds_dwordx4 v[12:13], off
	v_lshlrev_b64 v[12:13], 1, v[152:153]
	v_lshl_add_u64 v[14:15], s[16:17], 0, v[12:13]
	s_add_i32 m0, s37, 0x800
	v_mov_b32_e32 v155, v159
	global_load_lds_dwordx4 v[14:15], off
	v_lshlrev_b64 v[14:15], 1, v[154:155]
	v_lshl_add_u64 v[16:17], s[16:17], 0, v[14:15]
	s_add_i32 m0, s37, 0xc00
	v_mov_b32_e32 v157, v159
	global_load_lds_dwordx4 v[16:17], off
	v_lshlrev_b64 v[16:17], 1, v[156:157]
	v_lshl_add_u64 v[18:19], s[16:17], 0, v[16:17]
	s_add_i32 m0, s37, 0x1000
	v_mov_b32_e32 v3, v159
	global_load_lds_dwordx4 v[18:19], off
	v_lshlrev_b64 v[18:19], 1, v[158:159]
	v_lshl_add_u64 v[20:21], s[16:17], 0, v[18:19]
	s_add_i32 m0, s37, 0x1400
	v_lshlrev_b64 v[2:3], 1, v[2:3]
	v_mov_b32_e32 v5, v159
	global_load_lds_dwordx4 v[20:21], off
	v_lshl_add_u64 v[20:21], s[16:17], 0, v[2:3]
	s_add_i32 m0, s37, 0x1800
	v_lshlrev_b64 v[4:5], 1, v[4:5]
	s_lshr_b32 s39, s12, 8
	s_lshl_b32 s4, s13, 5
	global_load_lds_dwordx4 v[20:21], off
	v_lshl_add_u64 v[20:21], s[16:17], 0, v[4:5]
	s_lshl_b32 s16, s39, 6
	s_and_b32 s17, s4, 0x60
	s_xor_b32 s40, s17, s16
	s_lshl_b32 s4, s21, 7
	s_add_i32 m0, s37, 0x1c00
	s_add_i32 s41, s18, 0
	s_add_i32 s4, s4, s40
	s_add_u32 s4, s14, s4
	s_movk_i32 s38, 0x1400
	global_load_lds_dwordx4 v[20:21], off
	v_or_b32_e32 v7, s4, v1
	v_mov_b64_e32 v[20:21], s[8:9]
	v_mad_u64_u32 v[20:21], s[12:13], v7, s38, v[20:21]
	s_addc_u32 s14, s15, 0
	s_lshl_b32 s12, s26, 1
	s_and_b32 s12, s12, 2
	s_add_i32 s12, s12, s39
	v_mov_b32_e32 v204, 0x1400
	s_lshl_b32 s4, s22, 9
	s_lshl_b32 s12, s12, 7
	v_mad_i32_i24 v21, s14, v204, v21
	s_add_i32 s4, s12, s4
	v_lshl_add_u64 v[20:21], s[4:5], 1, v[20:21]
	v_mov_b32_e32 v147, v159
	v_lshl_add_u64 v[20:21], v[20:21], 0, v[146:147]
	global_load_dwordx4 v[98:101], v[20:21], off offset:224 nt
	global_load_dwordx4 v[102:105], v[20:21], off offset:192 nt
	global_load_dwordx4 v[106:109], v[20:21], off offset:160 nt
	global_load_dwordx4 v[110:113], v[20:21], off offset:128 nt
	global_load_dwordx4 v[114:117], v[20:21], off offset:96 nt
	global_load_dwordx4 v[118:121], v[20:21], off offset:64 nt
	global_load_dwordx4 v[122:125], v[20:21], off offset:32 nt
	global_load_dwordx4 v[126:129], v[20:21], off nt
	v_lshl_add_u64 v[168:169], s[6:7], 0, v[2:3]
	v_mov_b32_e32 v3, s16
	v_bitop3_b32 v3, s17, v1, v3 bitop3:0xde
	v_lshlrev_b32_e32 v7, 4, v137
	v_lshl_or_b32 v2, s39, 11, v146
	v_lshlrev_b32_e32 v3, 2, v3
	v_and_b32_e32 v21, 0xc0, v7
	v_lshlrev_b32_e32 v22, 1, v137
	s_movk_i32 s43, 0x70
	v_sub_u32_e32 v2, v2, v3
	s_movk_i32 s42, 0xc0
	v_lshlrev_b32_e32 v160, 3, v202
	v_and_b32_e32 v20, 0x78, v6
	v_and_b32_e32 v6, 0x118, v6
	v_and_b32_e32 v23, 0x70, v7
	v_bitop3_b32 v202, v146, v7, s43 bitop3:0x78
	s_movk_i32 s44, 0x60
	s_movk_i32 s45, 0x80
	s_movk_i32 s52, 0xa0
	s_movk_i32 s53, 0xe0
	v_and_or_b32 v7, v22, 32, v21
	v_add_u32_e32 v213, 0, v2
	v_mbcnt_lo_u32_b32 v2, -1, 0
	v_lshrrev_b32_e32 v162, 4, v161
	v_bitop3_b32 v205, v146, v23, 32 bitop3:0x36
	v_bitop3_b32 v206, v146, v23, 64 bitop3:0x36
	v_bitop3_b32 v207, v146, v23, s44 bitop3:0x36
	v_bitop3_b32 v208, v146, v23, s45 bitop3:0x36
	v_bitop3_b32 v209, v146, v23, s52 bitop3:0x36
	v_bitop3_b32 v210, v146, v23, s42 bitop3:0x36
	v_bitop3_b32 v211, v146, v23, s53 bitop3:0x36
	s_mov_b32 s54, 0x8000
	v_add3_u32 v212, v6, s20, v7
	v_lshl_add_u64 v[164:165], s[6:7], 0, v[4:5]
	v_lshl_add_u64 v[166:167], s[6:7], 0, v[18:19]
	v_lshl_add_u64 v[170:171], s[6:7], 0, v[8:9]
	v_lshl_add_u64 v[172:173], s[6:7], 0, v[10:11]
	v_lshl_add_u64 v[174:175], s[6:7], 0, v[12:13]
	v_lshl_add_u64 v[176:177], s[6:7], 0, v[14:15]
	v_lshl_add_u64 v[178:179], s[6:7], 0, v[16:17]
	v_mov_b32_e32 v215, 0x500
	v_lshlrev_b32_e32 v158, 1, v20
	s_mov_b64 s[12:13], 0xc00
	s_mov_b64 s[14:15], 0x5c00
	s_mov_b64 s[16:17], 0xac00
	s_mov_b64 s[18:19], 0xfc00
	s_add_i32 s55, 0, 0x24008
	s_mov_b32 s56, 0x10000
	s_mov_b32 s57, 0xf149f2ca
	s_mov_b32 s58, 0x41000000
	s_movk_i32 s59, 0x4000
	s_mov_b32 s74, 0x14000
	s_movk_i32 s75, 0x50
	s_movk_i32 s76, 0x90
	s_movk_i32 s77, 0xb0
	s_movk_i32 s78, 0xd0
	s_movk_i32 s79, 0xf0
	s_mov_b32 s80, 0xc000
	s_mov_b32 s81, 0x18000
	v_mbcnt_hi_u32_b32 v214, -1, v2
	s_mov_b32 s82, 0
	s_waitcnt vmcnt(0)
	s_branch .LBB0_1034

; #define LAS __attribute__((address_space(3)))
; DI void phase_attn(const Params& P, int l, LAS unsigned char* lds) {
;     ...
;     for (; item < AT_NITEM; ) {
;         const int half = item & 1, hk = (item >> 1) & 1, n = (item >> 2) & 31, sq = item >> 7;
;         const int g = hk * 4 + half * 2 + (wid >> 2), rq = n * 128 + ((wid & 3) ^ ((wid >> 2) << 1)) * 32;
;         const size_t tok = (size_t)sq * SEQL + rq + r32;
;         float m_run = P.sink[l * 8 + g] * LOG2E, l_run = 1.f;
;         f32x16 o[4]; for (int d = 0; d < 4; ++d) for (int i = 0; i < 16; ++i) o[d][i] = 0.f;
;         const int t_lo = n == 0 ? 1 : 0, t_hi = n == 31 ? 2 : 3;
;         const size_t tokw = (size_t)sq * SEQL + rq;
;         const bf16_t* zp = PA + (tokw + (lane >> 4)) * 2560 + 1536 + g * 128 + (lane & 15) * 8; u32x4 zz[8];
;         const LAS float* tg = tab + g * 512 + 96 + 128 - r32;
;         for (int t = t_lo; t < t_hi; ++t, ++e) {
.LBB0_1034:
	s_lshl_b32 s20, s26, 1
	s_bfe_u32 s27, s26, 0x10001
	s_and_b32 s20, s20, 2
	s_lshl_b32 s4, s27, 2
	s_add_i32 s20, s20, s39
	s_add_i32 s4, s20, s4
	s_lshl_b32 s20, s4, 2
	s_mov_b32 s67, s20
	v_mov_b32_e32 v2, s20
	v_readlane_b32 s20, v254, 0
	v_readlane_b32 s21, v254, 1
	s_bfe_u32 s64, s26, 0x50002
	s_lshl_b32 s71, s64, 7
	s_add_i32 s87, s71, s40
	v_readlane_b32 s22, v254, 2
	v_readlane_b32 s23, v254, 3
	s_add_i32 s67, s67, 32
	s_nop 4
	s_load_dword s68, s[20:21], s67
	s_ashr_i32 s20, s26, 7
	s_ashr_i32 s21, s20, 31
	s_lshl_b64 s[28:29], s[20:21], 12
	s_add_u32 s20, s28, s87
	s_addc_u32 s22, s29, 0
	s_cmp_eq_u32 s64, 31
	s_cselect_b32 s84, 2, 3
	s_lshl_b32 s83, s4, 7
	s_lshl_b32 s4, s4, 8
	s_cmp_eq_u32 s64, 0
	s_cselect_b64 s[30:31], -1, 0
	v_or_b32_e32 v146, s20, v162
	s_and_b64 s[20:21], s[30:31], exec
	v_mov_b64_e32 v[2:3], s[8:9]
	s_cselect_b32 s66, -2, -1
	s_cmpk_lt_i32 s36, 0x500
	v_mad_u64_u32 v[2:3], s[20:21], v146, s38, v[2:3]
	s_cselect_b64 s[24:25], -1, 0
	s_cmpk_gt_i32 s36, 0x4ff
	v_mov_b32_e32 v147, s22
	v_mad_i32_i24 v3, s22, v204, v3
	s_cselect_b64 s[20:21], -1, 0
	s_ashr_i32 s22, s36, 7
	s_bfe_i32 s23, s36, 0x10001
	v_lshl_add_u64 v[2:3], v[2:3], 0, s[4:5]
	s_and_b32 s35, s23, 0xa000
	s_ashr_i32 s23, s22, 31
	v_lshl_add_u64 v[2:3], v[2:3], 0, v[158:159]
	s_bfe_u32 s34, s36, 0x50002
	s_lshl_b64 s[22:23], s[22:23], 12
	v_lshl_add_u64 v[180:181], v[2:3], 0, s[12:13]
	v_lshl_add_u64 v[182:183], v[2:3], 0, s[14:15]
	v_lshl_add_u64 v[184:185], v[2:3], 0, s[16:17]
	v_lshl_add_u64 v[186:187], v[2:3], 0, s[18:19]
	v_sub_co_u32_e64 v2, vcc, s34, 1
	s_add_u32 s34, s35, s22
	s_mul_i32 s65, s27, 0xa000
	s_addc_u32 s35, 0, s23
	s_add_i32 s86, s87, 0xffffff80
	s_addk_i32 s87, 0x9f
	s_lshl_b32 s88, s82, 16
	v_addc_co_u32_e32 v2, vcc, 0, v2, vcc
	s_add_u32 s28, s65, s28
	v_lshlrev_b32_e32 v2, 7, v2
	s_addc_u32 s29, s29, 0
	v_ashrrev_i32_e32 v3, 31, v2
	s_cmp_lg_u64 s[30:31], 0
	v_lshl_add_u64 v[2:3], s[34:35], 0, v[2:3]
	s_addc_u32 s34, s64, 0
	s_lshl_b32 s34, s34, 7
	s_add_u32 s28, s28, s34
	s_addc_u32 s29, s29, 0
	s_and_b32 s35, s26, 1
	v_cndmask_b32_e64 v5, 0, 1, s[30:31]
	v_lshlrev_b64 v[188:189], 8, v[2:3]
	s_lshl_b32 s34, s27, 13
	s_lshl_b64 s[26:27], s[28:29], 8
	s_lshl_b32 s28, s35, 12
	v_lshlrev_b32_e32 v6, 9, v5
	v_lshl_add_u64 v[2:3], s[6:7], 0, v[188:189]
	s_or_b32 s28, s34, s28
	v_lshl_add_u64 v[190:191], v[148:149], 1, v[2:3]
	v_lshl_add_u64 v[192:193], v[150:151], 1, v[2:3]
	v_lshl_add_u64 v[194:195], v[152:153], 1, v[2:3]
	v_lshl_add_u64 v[196:197], v[154:155], 1, v[2:3]
	v_lshl_add_u64 v[198:199], v[156:157], 1, v[2:3]
	v_or_b32_e32 v2, s28, v6
	v_readfirstlane_b32 s4, v5
	s_cmp_lg_u64 s[30:31], 0
	v_add_u32_e32 v216, v213, v2
	v_subrev_u32_e32 v2, s84, v5
	v_mov_b32_e32 v16, v159
	v_mov_b32_e32 v17, v159
	s_addc_u32 s89, s66, 0
	v_add_u32_e32 v218, 1, v2
	s_lshl_b32 s28, s4, 7
	s_waitcnt lgkmcnt(0)
	v_mov_b32_e32 v4, s68
	v_mul_f32_e32 v217, 0x3fb8aa3b, v4
	v_mov_b32_e32 v2, v159
	v_mov_b32_e32 v3, v159
	v_mov_b32_e32 v4, v159
	v_mov_b32_e32 v5, v159
	v_mov_b32_e32 v6, v159
	v_mov_b32_e32 v7, v159
	v_mov_b32_e32 v8, v159
	v_mov_b32_e32 v9, v159
	v_mov_b32_e32 v10, v159
	v_mov_b32_e32 v11, v159
	v_mov_b32_e32 v12, v159
	v_mov_b32_e32 v13, v159
	v_mov_b32_e32 v14, v159
	v_mov_b32_e32 v15, v159
	v_mov_b64_e32 v[32:33], v[16:17]
	v_mov_b64_e32 v[48:49], v[16:17]
	v_mov_b64_e32 v[64:65], v[16:17]
	s_mov_b32 s70, 0
	s_add_i32 s90, s28, 0xffffff80
	v_mov_b32_e32 v219, 1.0
	s_mov_b32 s85, 0
	v_mov_b64_e32 v[30:31], v[14:15]
	v_mov_b64_e32 v[28:29], v[12:13]
	v_mov_b64_e32 v[26:27], v[10:11]
	v_mov_b64_e32 v[24:25], v[8:9]
	v_mov_b64_e32 v[22:23], v[6:7]
	v_mov_b64_e32 v[20:21], v[4:5]
	v_mov_b64_e32 v[18:19], v[2:3]
	v_mov_b64_e32 v[46:47], v[14:15]
	v_mov_b64_e32 v[44:45], v[12:13]
	v_mov_b64_e32 v[42:43], v[10:11]
	v_mov_b64_e32 v[40:41], v[8:9]
	v_mov_b64_e32 v[38:39], v[6:7]
	v_mov_b64_e32 v[36:37], v[4:5]
	v_mov_b64_e32 v[34:35], v[2:3]
	v_mov_b64_e32 v[62:63], v[14:15]
	v_mov_b64_e32 v[60:61], v[12:13]
	v_mov_b64_e32 v[58:59], v[10:11]
	v_mov_b64_e32 v[56:57], v[8:9]
	v_mov_b64_e32 v[54:55], v[6:7]
	v_mov_b64_e32 v[52:53], v[4:5]
	v_mov_b64_e32 v[50:51], v[2:3]
	s_waitcnt vmcnt(8)
	s_add_i32 s28, s89, s85
	s_branch .Lat_first_1

; DI void phase_attn(const Params& P, int l, LAS unsigned char* lds) {
;     ...
;             asm volatile("s_waitcnt vmcnt(0)" ::: "memory");
;             if (t == t_lo + 1 && tid == 0) slot[2] = pend;
;             asm volatile("s_waitcnt lgkmcnt(0)" ::: "memory");
;             __builtin_amdgcn_s_barrier();
;             asm volatile("" ::: "memory");
;             if (t == t_lo && tid == 0) pend = (int)__hip_atomic_fetch_add(qctr, 1u, __ATOMIC_RELAXED, __HIP_MEMORY_SCOPE_AGENT);
.Lat_first_1:
	s_cmp_eq_u32 s28, 0
	s_cselect_b64 s[28:29], -1, 0
	s_and_b64 s[30:31], s[0:1], s[28:29]
	s_and_saveexec_b64 s[28:29], s[30:31]
	v_mov_b32_e32 v66, s55
	v_mov_b32_e32 v215, v255
	ds_write_b32 v66, v215
	s_or_b64 exec, exec, s[28:29]
	s_waitcnt lgkmcnt(0)
	s_barrier
	s_cmp_eq_u32 s70, 0
	s_cselect_b64 s[28:29], -1, 0
	s_and_b64 s[30:31], s[0:1], s[28:29]
	s_and_saveexec_b64 s[28:29], s[30:31]
	s_cbranch_execz .LBB0_1043
	s_mov_b64 s[34:35], exec
	v_mbcnt_lo_u32_b32 v66, s34, 0
	v_mbcnt_hi_u32_b32 v66, s35, v66
	v_cmp_eq_u32_e32 vcc, 0, v66
	s_and_saveexec_b64 s[30:31], vcc
	s_cbranch_execz .LBB0_1042
	s_bcnt1_i32_b64 s34, s[34:35]
	v_mov_b32_e32 v67, s34
	global_atomic_add v255, v159, v67, s[2:3] sc0
